# ATT0 hosts exactly two weight-transpose items per workgroup; the last 80 WD0 items run at the start of GU0 on workgroups 128..207 and are published through a counter that barrier 7 checks
# speedup vs baseline: 1.0107x; 1.0107x over previous
.LBB0_326:
	s_or_b64 exec, exec, s[4:5]
	v_readlane_b32 s0, v219, 9
	v_lshlrev_b32_e32 v20, 2, v149
	v_readlane_b32 s8, v219, 17
	v_readlane_b32 s9, v219, 18
	s_waitcnt lgkmcnt(0)
	s_barrier
	s_nop 2
	global_load_dword v0, v20, s[8:9]
	global_load_dword v1, v20, s[8:9] offset:256
	global_load_dword v2, v20, s[8:9] offset:512
	global_load_dword v3, v20, s[8:9] offset:768
	v_mbcnt_hi_u32_b32 v4, -1, v163
	v_and_b32_e32 v5, 64, v4
	v_xor_b32_e32 v6, 32, v4
	v_add_u32_e32 v5, 64, v5
	v_cmp_lt_i32_e32 vcc, v6, v5
	v_xor_b32_e32 v7, 16, v4
	v_xor_b32_e32 v8, 8, v4
	v_cndmask_b32_e32 v6, v4, v6, vcc
	v_lshlrev_b32_e32 v172, 2, v6
	v_cmp_lt_i32_e32 vcc, v7, v5
	v_xor_b32_e32 v9, 4, v4
	v_xor_b32_e32 v10, 2, v4
	v_cndmask_b32_e32 v7, v4, v7, vcc
	v_lshlrev_b32_e32 v173, 2, v7
	v_cmp_lt_i32_e32 vcc, v8, v5
	v_xor_b32_e32 v11, 1, v4
	s_bcnt1_i32_b32 s0, s78
	s_bitcmp0_b32 s0, 0
	s_cselect_b64 s[8:9], -1, 0
	v_readlane_b32 s1, v219, 10
	v_readlane_b32 s2, v219, 11
	v_readlane_b32 s3, v219, 12
	v_readlane_b32 s4, v219, 13
	v_readlane_b32 s5, v219, 14
	v_readlane_b32 s6, v219, 15
	v_readlane_b32 s7, v219, 16
	v_readlane_b32 s10, v219, 19
	v_readlane_b32 s11, v219, 20
	v_readlane_b32 s12, v219, 21
	v_readlane_b32 s13, v219, 22
	v_readlane_b32 s14, v219, 23
	v_readlane_b32 s15, v219, 24
	s_waitcnt vmcnt(2)
	v_mul_f32_e32 v6, v0, v1
	ds_bpermute_b32 v6, v172, v6
	s_waitcnt vmcnt(0)
	v_mul_f32_e32 v12, v2, v3
	ds_bpermute_b32 v12, v172, v12
	s_waitcnt lgkmcnt(1)
	v_fmac_f32_e32 v6, v0, v1
	ds_bpermute_b32 v0, v173, v6
	s_waitcnt lgkmcnt(1)
	v_fmac_f32_e32 v12, v2, v3
	ds_bpermute_b32 v1, v173, v12
	v_cndmask_b32_e32 v2, v4, v8, vcc
	v_lshlrev_b32_e32 v174, 2, v2
	s_waitcnt lgkmcnt(1)
	v_add_f32_e32 v0, v6, v0
	ds_bpermute_b32 v2, v174, v0
	s_waitcnt lgkmcnt(1)
	v_add_f32_e32 v1, v12, v1
	ds_bpermute_b32 v3, v174, v1
	v_cmp_lt_i32_e32 vcc, v9, v5
	s_waitcnt lgkmcnt(1)
	v_add_f32_e32 v0, v0, v2
	v_cndmask_b32_e32 v6, v4, v9, vcc
	v_lshlrev_b32_e32 v175, 2, v6
	s_waitcnt lgkmcnt(0)
	v_add_f32_e32 v1, v1, v3
	ds_bpermute_b32 v2, v175, v0
	ds_bpermute_b32 v3, v175, v1
	v_cmp_lt_i32_e32 vcc, v10, v5
	s_waitcnt lgkmcnt(1)
	v_add_f32_e32 v0, v0, v2
	v_cndmask_b32_e32 v6, v4, v10, vcc
	v_lshlrev_b32_e32 v176, 2, v6
	s_waitcnt lgkmcnt(0)
	v_add_f32_e32 v1, v1, v3
	ds_bpermute_b32 v2, v176, v0
	ds_bpermute_b32 v3, v176, v1
	v_cmp_lt_i32_e32 vcc, v11, v5
	s_waitcnt lgkmcnt(1)
	v_add_f32_e32 v21, v0, v2
	v_cndmask_b32_e32 v4, v4, v11, vcc
	v_lshlrev_b32_e32 v177, 2, v4
	s_waitcnt lgkmcnt(0)
	v_add_f32_e32 v22, v1, v3
	ds_bpermute_b32 v23, v177, v21
	ds_bpermute_b32 v24, v177, v22
	s_and_b64 vcc, exec, s[8:9]
	s_cbranch_vccnz .LBB0_347
	s_add_i32 s0, s78, 0xc0
	s_cmpk_gt_i32 s0, 0x2bf
	s_waitcnt lgkmcnt(0)
	s_barrier
	s_cbranch_scc1 .LBB0_346
	s_movk_i32 s1, 0x2100
	v_lshrrev_b32_e32 v25, 3, v149
	v_and_b32_e32 v4, 56, v144
	s_cmpk_eq_i32 s58, 0x100
	v_mad_u32_u24 v1, v148, s1, 0
	v_lshrrev_b32_e32 v0, 5, v149
	v_and_b32_e32 v2, 31, v168
	v_mul_u32_u24_e32 v3, 0x84, v4
	v_lshlrev_b32_e32 v7, 2, v25
	s_cselect_b64 s[6:7], -1, 0
	v_mov_b32_e32 v5, 0
	v_lshl_add_u32 v6, v2, 2, v1
	s_movk_i32 s1, 0x84
	v_add3_u32 v26, v1, v3, v7
	v_or_b32_e32 v27, 8, v25
	v_or_b32_e32 v28, 16, v25
	v_or_b32_e32 v29, 24, v25
	v_mov_b32_e32 v1, v0
	s_movk_i32 s2, 0x187f
	s_movk_i32 s3, 0x1ff
	s_movk_i32 s10, 0xcff
	v_lshlrev_b32_e32 v8, 2, v2
	v_lshlrev_b32_e32 v10, 1, v4
	v_mov_b32_e32 v30, 0xffffe780
	v_mov_b32_e32 v31, 0xc00
	v_mov_b32_e32 v32, 0x600
	v_mov_b32_e32 v33, 0x2c0000
	v_mov_b32_e32 v34, 0x1400000
	v_mov_b32_e32 v35, 0x2980000
	v_mov_b32_e32 v36, 0x900000
	v_mov_b32_e32 v37, 0x1e80000
	v_mov_b32_e32 v38, 0x700000
	v_mov_b32_e32 v39, 0x1c80000
	v_mov_b32_e32 v40, 0x100000
	v_mov_b32_e32 v41, 0x1980000
	s_branch .LBB0_330
.LBB0_329:
	s_add_i32 s0, s0, s58
	s_cmpk_lt_i32 s0, 0x2c0
	s_cbranch_scc0 .LBB0_346

.LBB0_375:
	s_and_b64 vcc, exec, s[8:9]
	s_cbranch_vccz .LBB0_396
	s_add_i32 s0, s78, 0xc0
	s_cmpk_gt_i32 s0, 0x2bf
	s_waitcnt lgkmcnt(0)
	s_barrier
	s_cbranch_scc1 .LBB0_395
	s_movk_i32 s1, 0x2100
	v_lshrrev_b32_e32 v20, 3, v149
	v_and_b32_e32 v4, 56, v144
	s_cmpk_eq_i32 s58, 0x100
	v_mad_u32_u24 v1, v148, s1, 0
	v_lshrrev_b32_e32 v0, 5, v149
	v_and_b32_e32 v2, 31, v168
	v_mul_u32_u24_e32 v3, 0x84, v4
	v_lshlrev_b32_e32 v7, 2, v20
	s_cselect_b64 s[6:7], -1, 0
	v_mov_b32_e32 v5, 0
	v_lshl_add_u32 v6, v2, 2, v1
	s_movk_i32 s1, 0x84
	v_add3_u32 v21, v1, v3, v7
	v_or_b32_e32 v22, 8, v20
	v_or_b32_e32 v23, 16, v20
	v_or_b32_e32 v24, 24, v20
	v_mov_b32_e32 v1, v0
	s_movk_i32 s2, 0x187f
	s_movk_i32 s3, 0x1ff
	s_movk_i32 s10, 0xcff
	v_lshlrev_b32_e32 v8, 2, v2
	v_lshlrev_b32_e32 v10, 1, v4
	v_mov_b32_e32 v25, 0xffffe780
	v_mov_b32_e32 v26, 0xc00
	v_mov_b32_e32 v27, 0x600
	v_mov_b32_e32 v28, 0x2c0000
	v_mov_b32_e32 v29, 0x1400000
	v_mov_b32_e32 v30, 0x2980000
	v_mov_b32_e32 v31, 0x900000
	v_mov_b32_e32 v32, 0x1e80000
	v_mov_b32_e32 v33, 0x700000
	v_mov_b32_e32 v34, 0x1c80000
	v_mov_b32_e32 v35, 0x100000
	v_mov_b32_e32 v36, 0x1980000
	s_branch .LBB0_379

.LBB0_629:
	s_or_b64 exec, exec, s[4:5]
	s_cmpk_lt_i32 s78, 0x580
	s_cselect_b64 s[0:1], -1, 0
	v_writelane_b32 v219, s0, 52
	s_cmpk_gt_i32 s78, 0x57f
	v_readfirstlane_b32 s4, v168
	s_waitcnt lgkmcnt(0)
	s_barrier
	v_mov_b32_e32 v222, 0
	v_writelane_b32 v219, s1, 53
	v_readlane_b32 s78, v219, 30
	s_nop 3
	s_cmpk_lt_u32 s78, 0x80
	s_cbranch_scc1 .Lgu0e_skip
	v_writelane_b32 v220, s0, 0
	v_writelane_b32 v220, s1, 1
	v_writelane_b32 v220, s2, 2
	v_writelane_b32 v220, s3, 3
	v_writelane_b32 v220, s4, 4
	v_writelane_b32 v220, s5, 5
	v_writelane_b32 v220, s6, 6
	v_writelane_b32 v220, s7, 7
	v_writelane_b32 v220, s8, 8
	v_writelane_b32 v220, s9, 9
	v_writelane_b32 v220, s10, 10
	v_writelane_b32 v220, s11, 11
	v_writelane_b32 v220, s12, 12
	v_writelane_b32 v220, s13, 13
	v_writelane_b32 v220, s14, 14
	v_writelane_b32 v220, s15, 15
	v_writelane_b32 v220, s16, 16
	v_writelane_b32 v220, s17, 17
	v_writelane_b32 v220, s18, 18
	v_writelane_b32 v220, s19, 19
	v_writelane_b32 v220, s20, 20
	v_writelane_b32 v220, s21, 21
	v_writelane_b32 v220, s22, 22
	v_writelane_b32 v220, s23, 23
	v_writelane_b32 v220, s24, 24
	v_writelane_b32 v220, s25, 25
	v_writelane_b32 v220, s26, 26
	v_writelane_b32 v220, s27, 27
	v_writelane_b32 v220, s36, 28
	v_writelane_b32 v220, s37, 29
	v_writelane_b32 v220, s38, 30
	v_writelane_b32 v220, s39, 31
	v_writelane_b32 v220, s40, 32
	v_writelane_b32 v220, s41, 33
	v_writelane_b32 v220, s42, 34
	v_writelane_b32 v220, s43, 35
	v_writelane_b32 v220, s44, 36
	v_writelane_b32 v220, s45, 37
	v_writelane_b32 v220, s46, 38
	v_writelane_b32 v220, s47, 39
	v_writelane_b32 v220, s48, 40
	v_writelane_b32 v220, s49, 41
	v_writelane_b32 v220, s50, 42
	v_writelane_b32 v220, s51, 43
	s_cmpk_gt_i32 s78, 0xcf
	s_waitcnt vmcnt(0) lgkmcnt(0)
	s_barrier
	s_cbranch_scc1 .Lgu0e_BB0_1034
	s_movk_i32 s1, 0x2100
	v_and_b32_e32 v4, 56, v144
	v_mad_u32_u24 v1, v148, s1, 0
	v_lshrrev_b32_e32 v0, 5, v149
	v_and_b32_e32 v2, 31, v168
	v_mul_u32_u24_e32 v3, 0x84, v4
	v_lshlrev_b32_e32 v7, 2, v185
	s_add_i32 s0, s78, 0x240
	v_mov_b32_e32 v5, 0
	v_lshl_add_u32 v6, v2, 2, v1
	s_movk_i32 s1, 0x84
	v_add3_u32 v20, v1, v3, v7
	v_or_b32_e32 v21, 8, v185
	v_or_b32_e32 v22, 16, v185
	v_or_b32_e32 v23, 24, v185
	v_mov_b32_e32 v1, v0
	s_movk_i32 s2, 0x187f
	v_mov_b32_e32 v24, 0xffffe780
	v_mov_b32_e32 v25, 0xc00
	v_mov_b32_e32 v26, 0x600
	s_movk_i32 s3, 0x1ff
	s_movk_i32 s4, 0xcff
	v_lshlrev_b32_e32 v8, 2, v2
	v_lshlrev_b32_e32 v10, 1, v4
	v_mov_b32_e32 v27, 0x2c0000
	v_mov_b32_e32 v28, 0x1400000
	v_mov_b32_e32 v29, 0x2980000
	v_mov_b32_e32 v30, 0x900000
	v_mov_b32_e32 v31, 0x1e80000
	v_mov_b32_e32 v32, 0x700000
	v_mov_b32_e32 v33, 0x1c80000
	v_mov_b32_e32 v34, 0x100000
	v_mov_b32_e32 v35, 0x1980000

.Lgu0e_BB0_1032:
	s_lshl_b32 s8, s6, 1
	s_lshl_b32 s9, s5, 1
	v_or_b32_e32 v9, s8, v1
	v_or_b32_e32 v11, s9, v0
	s_add_i32 s10, s8, 4
	s_add_i32 s11, s9, 4
	s_add_i32 s12, s8, 8
	s_add_i32 s13, s9, 8
	s_add_i32 s14, s8, 12
	s_add_i32 s15, s9, 12
	s_add_i32 s16, s8, 16
	s_add_i32 s17, s9, 16
	s_add_i32 s18, s8, 20
	s_add_i32 s19, s9, 20
	s_add_i32 s20, s8, 24
	s_add_i32 s21, s9, 24
	s_add_i32 s8, s8, 28
	s_add_i32 s9, s9, 28
	v_add_u32_e32 v17, v9, v7
	v_add_u32_e32 v37, v11, v16
	v_or_b32_e32 v70, s10, v1
	v_or_b32_e32 v71, s11, v0
	v_or_b32_e32 v72, s12, v1
	v_or_b32_e32 v73, s13, v0
	v_or_b32_e32 v74, s14, v1
	v_or_b32_e32 v75, s15, v0
	v_or_b32_e32 v76, s16, v1
	v_or_b32_e32 v77, s17, v0
	v_or_b32_e32 v78, s18, v1
	v_or_b32_e32 v79, s19, v0
	v_or_b32_e32 v80, s20, v1
	v_or_b32_e32 v81, s21, v0
	v_or_b32_e32 v82, s8, v1
	v_or_b32_e32 v83, s9, v0
	v_ashrrev_i32_e32 v42, 31, v37
	v_ashrrev_i32_e32 v43, 31, v17
	v_mul_lo_u32 v84, v3, v17
	v_mad_u64_u32 v[38:39], s[8:9], v2, v17, 0
	v_mul_lo_u32 v17, v13, v37
	v_mad_u64_u32 v[40:41], s[8:9], v12, v37, 0
	v_add_u32_e32 v37, v70, v7
	v_add_u32_e32 v44, v71, v16
	v_add_u32_e32 v46, v72, v7
	v_add_u32_e32 v48, v73, v16
	v_add_u32_e32 v50, v74, v7
	v_add_u32_e32 v52, v75, v16
	v_add_u32_e32 v54, v76, v7
	v_add_u32_e32 v56, v77, v16
	v_add_u32_e32 v58, v78, v7
	v_add_u32_e32 v60, v79, v16
	v_add_u32_e32 v62, v80, v7
	v_add_u32_e32 v64, v81, v16
	v_add_u32_e32 v66, v82, v7
	v_add_u32_e32 v68, v83, v16
	v_mul_lo_u32 v85, v2, v43
	v_mul_lo_u32 v86, v12, v42
	v_ashrrev_i32_e32 v87, 31, v44
	v_ashrrev_i32_e32 v88, 31, v37
	v_ashrrev_i32_e32 v90, 31, v48
	v_ashrrev_i32_e32 v91, 31, v46
	v_ashrrev_i32_e32 v94, 31, v52
	v_ashrrev_i32_e32 v95, 31, v50
	v_ashrrev_i32_e32 v98, 31, v56
	v_ashrrev_i32_e32 v99, 31, v54
	v_ashrrev_i32_e32 v102, 31, v60
	v_ashrrev_i32_e32 v103, 31, v58
	v_ashrrev_i32_e32 v106, 31, v64
	v_ashrrev_i32_e32 v107, 31, v62
	v_ashrrev_i32_e32 v110, 31, v68
	v_ashrrev_i32_e32 v111, 31, v66
	v_mul_lo_u32 v89, v3, v37
	v_mad_u64_u32 v[42:43], s[8:9], v2, v37, 0
	v_mul_lo_u32 v37, v13, v44
	v_mad_u64_u32 v[44:45], s[8:9], v12, v44, 0
	v_mul_lo_u32 v92, v3, v46
	v_mad_u64_u32 v[46:47], s[8:9], v2, v46, 0
	v_mul_lo_u32 v93, v13, v48
	v_mad_u64_u32 v[48:49], s[8:9], v12, v48, 0
	v_mul_lo_u32 v96, v3, v50
	v_mad_u64_u32 v[50:51], s[8:9], v2, v50, 0
	v_mul_lo_u32 v97, v13, v52
	v_mad_u64_u32 v[52:53], s[8:9], v12, v52, 0
	v_mul_lo_u32 v100, v3, v54
	v_mad_u64_u32 v[54:55], s[8:9], v2, v54, 0
	v_mul_lo_u32 v101, v13, v56
	v_mad_u64_u32 v[56:57], s[8:9], v12, v56, 0
	v_mul_lo_u32 v104, v3, v58
	v_mad_u64_u32 v[58:59], s[8:9], v2, v58, 0
	v_mul_lo_u32 v105, v13, v60
	v_mad_u64_u32 v[60:61], s[8:9], v12, v60, 0
	v_mul_lo_u32 v108, v3, v62
	v_mad_u64_u32 v[62:63], s[8:9], v2, v62, 0
	v_mul_lo_u32 v109, v13, v64
	v_mad_u64_u32 v[64:65], s[8:9], v12, v64, 0
	v_mul_lo_u32 v112, v3, v66
	v_mad_u64_u32 v[66:67], s[8:9], v2, v66, 0
	v_mul_lo_u32 v113, v13, v68
	v_mad_u64_u32 v[68:69], s[8:9], v12, v68, 0
	v_add3_u32 v39, v39, v85, v84
	v_add3_u32 v41, v41, v86, v17
	v_mul_lo_u32 v17, v2, v88
	v_mul_lo_u32 v84, v12, v87
	v_mul_lo_u32 v85, v2, v91
	v_mul_lo_u32 v86, v12, v90
	v_mul_lo_u32 v87, v2, v95
	v_mul_lo_u32 v88, v12, v94
	v_mul_lo_u32 v90, v2, v99
	v_mul_lo_u32 v91, v12, v98
	v_mul_lo_u32 v94, v2, v103
	v_mul_lo_u32 v95, v12, v102
	v_mul_lo_u32 v98, v2, v107
	v_mul_lo_u32 v99, v12, v106
	v_mul_lo_u32 v102, v2, v111
	v_mul_lo_u32 v103, v12, v110
	v_lshl_add_u64 v[40:41], v[40:41], 2, v[18:19]
	v_add3_u32 v43, v43, v17, v89
	v_add3_u32 v45, v45, v84, v37
	v_add3_u32 v47, v47, v85, v92
	v_add3_u32 v49, v49, v86, v93
	v_add3_u32 v51, v51, v87, v96
	v_add3_u32 v53, v53, v88, v97
	v_add3_u32 v55, v55, v90, v100
	v_add3_u32 v57, v57, v91, v101
	v_add3_u32 v59, v59, v94, v104
	v_add3_u32 v61, v61, v95, v105
	v_add3_u32 v63, v63, v98, v108
	v_add3_u32 v65, v65, v99, v109
	v_add3_u32 v67, v67, v102, v112
	v_add3_u32 v69, v69, v103, v113
	v_lshl_add_u64 v[38:39], v[38:39], 2, v[18:19]
	v_lshl_add_u64 v[44:45], v[44:45], 2, v[18:19]
	v_lshl_add_u64 v[42:43], v[42:43], 2, v[18:19]
	v_lshl_add_u64 v[48:49], v[48:49], 2, v[18:19]
	v_lshl_add_u64 v[46:47], v[46:47], 2, v[18:19]
	v_lshl_add_u64 v[52:53], v[52:53], 2, v[18:19]
	v_lshl_add_u64 v[50:51], v[50:51], 2, v[18:19]
	v_lshl_add_u64 v[56:57], v[56:57], 2, v[18:19]
	v_lshl_add_u64 v[54:55], v[54:55], 2, v[18:19]
	v_lshl_add_u64 v[60:61], v[60:61], 2, v[18:19]
	v_lshl_add_u64 v[58:59], v[58:59], 2, v[18:19]
	v_lshl_add_u64 v[64:65], v[64:65], 2, v[18:19]
	v_lshl_add_u64 v[62:63], v[62:63], 2, v[18:19]
	v_lshl_add_u64 v[68:69], v[68:69], 2, v[18:19]
	v_lshl_add_u64 v[66:67], v[66:67], 2, v[18:19]
	global_load_dword v17, v[40:41], off nt
	global_load_dword v37, v[38:39], off nt
	global_load_dword v84, v[44:45], off nt
	global_load_dword v85, v[42:43], off nt
	global_load_dword v86, v[48:49], off nt
	global_load_dword v87, v[46:47], off nt
	global_load_dword v88, v[52:53], off nt
	global_load_dword v89, v[50:51], off nt
	global_load_dword v90, v[56:57], off nt
	global_load_dword v91, v[54:55], off nt
	global_load_dword v92, v[60:61], off nt
	global_load_dword v93, v[58:59], off nt
	global_load_dword v94, v[64:65], off nt
	global_load_dword v95, v[62:63], off nt
	global_load_dword v96, v[68:69], off nt
	global_load_dword v97, v[66:67], off nt
	s_add_i32 s5, s5, 16
	s_add_i32 s6, s6, 16
	v_mad_u64_u32 v[38:39], s[8:9], v11, s1, v[6:7]
	v_mad_u64_u32 v[40:41], s[8:9], v9, s1, v[6:7]
	v_mad_u64_u32 v[42:43], s[8:9], v71, s1, v[6:7]
	v_mad_u64_u32 v[44:45], s[8:9], v70, s1, v[6:7]
	v_mad_u64_u32 v[46:47], s[8:9], v73, s1, v[6:7]
	v_mad_u64_u32 v[48:49], s[8:9], v72, s1, v[6:7]
	v_mad_u64_u32 v[50:51], s[8:9], v75, s1, v[6:7]
	v_mad_u64_u32 v[52:53], s[8:9], v74, s1, v[6:7]
	v_mad_u64_u32 v[54:55], s[8:9], v77, s1, v[6:7]
	v_mad_u64_u32 v[56:57], s[8:9], v76, s1, v[6:7]
	v_mad_u64_u32 v[58:59], s[8:9], v79, s1, v[6:7]
	v_mad_u64_u32 v[60:61], s[8:9], v78, s1, v[6:7]
	v_mad_u64_u32 v[62:63], s[8:9], v81, s1, v[6:7]
	v_mad_u64_u32 v[64:65], s[8:9], v80, s1, v[6:7]
	v_mad_u64_u32 v[66:67], s[8:9], v83, s1, v[6:7]
	v_mad_u64_u32 v[68:69], s[8:9], v82, s1, v[6:7]
	s_lshl_b32 s8, s6, 1
	s_lshl_b32 s9, s5, 1
	v_or_b32_e32 v9, s8, v1
	v_or_b32_e32 v11, s9, v0
	s_add_i32 s10, s8, 4
	s_add_i32 s11, s9, 4
	s_add_i32 s12, s8, 8
	s_add_i32 s13, s9, 8
	s_add_i32 s14, s8, 12
	s_add_i32 s15, s9, 12
	s_add_i32 s16, s8, 16
	s_add_i32 s17, s9, 16
	s_add_i32 s18, s8, 20
	s_add_i32 s19, s9, 20
	s_add_i32 s20, s8, 24
	s_add_i32 s21, s9, 24
	s_add_i32 s8, s8, 28
	s_add_i32 s9, s9, 28
	v_add_u32_e32 v120, v9, v7
	v_add_u32_e32 v121, v11, v16
	v_or_b32_e32 v70, s10, v1
	v_or_b32_e32 v71, s11, v0
	v_or_b32_e32 v72, s12, v1
	v_or_b32_e32 v73, s13, v0
	v_or_b32_e32 v74, s14, v1
	v_or_b32_e32 v75, s15, v0
	v_or_b32_e32 v76, s16, v1
	v_or_b32_e32 v77, s17, v0
	v_or_b32_e32 v78, s18, v1
	v_or_b32_e32 v79, s19, v0
	v_or_b32_e32 v80, s20, v1
	v_or_b32_e32 v81, s21, v0
	v_or_b32_e32 v82, s8, v1
	v_or_b32_e32 v83, s9, v0
	v_ashrrev_i32_e32 v190, 31, v121
	v_ashrrev_i32_e32 v191, 31, v120
	v_mul_lo_u32 v122, v3, v120
	v_mad_u64_u32 v[186:187], s[8:9], v2, v120, 0
	v_mul_lo_u32 v120, v13, v121
	v_mad_u64_u32 v[188:189], s[8:9], v12, v121, 0
	v_add_u32_e32 v121, v70, v7
	v_add_u32_e32 v192, v71, v16
	v_add_u32_e32 v194, v72, v7
	v_add_u32_e32 v196, v73, v16
	v_add_u32_e32 v198, v74, v7
	v_add_u32_e32 v200, v75, v16
	v_add_u32_e32 v202, v76, v7
	v_add_u32_e32 v204, v77, v16
	v_add_u32_e32 v206, v78, v7
	v_add_u32_e32 v208, v79, v16
	v_add_u32_e32 v210, v80, v7
	v_add_u32_e32 v212, v81, v16
	v_add_u32_e32 v214, v82, v7
	v_add_u32_e32 v216, v83, v16
	v_mul_lo_u32 v123, v2, v191
	v_mul_lo_u32 v124, v12, v190
	v_ashrrev_i32_e32 v125, 31, v192
	v_ashrrev_i32_e32 v126, 31, v121
	v_ashrrev_i32_e32 v128, 31, v196
	v_ashrrev_i32_e32 v129, 31, v194
	v_ashrrev_i32_e32 v132, 31, v200
	v_ashrrev_i32_e32 v133, 31, v198
	v_ashrrev_i32_e32 v98, 31, v204
	v_ashrrev_i32_e32 v99, 31, v202
	v_ashrrev_i32_e32 v102, 31, v208
	v_ashrrev_i32_e32 v103, 31, v206
	v_ashrrev_i32_e32 v106, 31, v212
	v_ashrrev_i32_e32 v107, 31, v210
	v_ashrrev_i32_e32 v110, 31, v216
	v_ashrrev_i32_e32 v111, 31, v214
	v_mul_lo_u32 v127, v3, v121
	v_mad_u64_u32 v[190:191], s[8:9], v2, v121, 0
	v_mul_lo_u32 v121, v13, v192
	v_mad_u64_u32 v[192:193], s[8:9], v12, v192, 0
	v_mul_lo_u32 v130, v3, v194
	v_mad_u64_u32 v[194:195], s[8:9], v2, v194, 0
	v_mul_lo_u32 v131, v13, v196
	v_mad_u64_u32 v[196:197], s[8:9], v12, v196, 0
	v_mul_lo_u32 v134, v3, v198
	v_mad_u64_u32 v[198:199], s[8:9], v2, v198, 0
	v_mul_lo_u32 v135, v13, v200
	v_mad_u64_u32 v[200:201], s[8:9], v12, v200, 0
	v_mul_lo_u32 v100, v3, v202
	v_mad_u64_u32 v[202:203], s[8:9], v2, v202, 0
	v_mul_lo_u32 v101, v13, v204
	v_mad_u64_u32 v[204:205], s[8:9], v12, v204, 0
	v_mul_lo_u32 v104, v3, v206
	v_mad_u64_u32 v[206:207], s[8:9], v2, v206, 0
	v_mul_lo_u32 v105, v13, v208
	v_mad_u64_u32 v[208:209], s[8:9], v12, v208, 0
	v_mul_lo_u32 v108, v3, v210
	v_mad_u64_u32 v[210:211], s[8:9], v2, v210, 0
	v_mul_lo_u32 v109, v13, v212
	v_mad_u64_u32 v[212:213], s[8:9], v12, v212, 0
	v_mul_lo_u32 v112, v3, v214
	v_mad_u64_u32 v[214:215], s[8:9], v2, v214, 0
	v_mul_lo_u32 v113, v13, v216
	v_mad_u64_u32 v[216:217], s[8:9], v12, v216, 0
	v_add3_u32 v187, v187, v123, v122
	v_add3_u32 v189, v189, v124, v120
	v_mul_lo_u32 v120, v2, v126
	v_mul_lo_u32 v122, v12, v125
	v_mul_lo_u32 v123, v2, v129
	v_mul_lo_u32 v124, v12, v128
	v_mul_lo_u32 v125, v2, v133
	v_mul_lo_u32 v126, v12, v132
	v_mul_lo_u32 v128, v2, v99
	v_mul_lo_u32 v129, v12, v98
	v_mul_lo_u32 v132, v2, v103
	v_mul_lo_u32 v133, v12, v102
	v_mul_lo_u32 v98, v2, v107
	v_mul_lo_u32 v99, v12, v106
	v_mul_lo_u32 v102, v2, v111
	v_mul_lo_u32 v103, v12, v110
	v_lshl_add_u64 v[188:189], v[188:189], 2, v[18:19]
	v_add3_u32 v191, v191, v120, v127
	v_add3_u32 v193, v193, v122, v121
	v_add3_u32 v195, v195, v123, v130
	v_add3_u32 v197, v197, v124, v131
	v_add3_u32 v199, v199, v125, v134
	v_add3_u32 v201, v201, v126, v135
	v_add3_u32 v203, v203, v128, v100
	v_add3_u32 v205, v205, v129, v101
	v_add3_u32 v207, v207, v132, v104
	v_add3_u32 v209, v209, v133, v105
	v_add3_u32 v211, v211, v98, v108
	v_add3_u32 v213, v213, v99, v109
	v_add3_u32 v215, v215, v102, v112
	v_add3_u32 v217, v217, v103, v113
	v_lshl_add_u64 v[186:187], v[186:187], 2, v[18:19]
	v_lshl_add_u64 v[192:193], v[192:193], 2, v[18:19]
	v_lshl_add_u64 v[190:191], v[190:191], 2, v[18:19]
	v_lshl_add_u64 v[196:197], v[196:197], 2, v[18:19]
	v_lshl_add_u64 v[194:195], v[194:195], 2, v[18:19]
	v_lshl_add_u64 v[200:201], v[200:201], 2, v[18:19]
	v_lshl_add_u64 v[198:199], v[198:199], 2, v[18:19]
	v_lshl_add_u64 v[204:205], v[204:205], 2, v[18:19]
	v_lshl_add_u64 v[202:203], v[202:203], 2, v[18:19]
	v_lshl_add_u64 v[208:209], v[208:209], 2, v[18:19]
	v_lshl_add_u64 v[206:207], v[206:207], 2, v[18:19]
	v_lshl_add_u64 v[212:213], v[212:213], 2, v[18:19]
	v_lshl_add_u64 v[210:211], v[210:211], 2, v[18:19]
	v_lshl_add_u64 v[216:217], v[216:217], 2, v[18:19]
	v_lshl_add_u64 v[214:215], v[214:215], 2, v[18:19]
	global_load_dword v120, v[188:189], off nt
	global_load_dword v121, v[186:187], off nt
	global_load_dword v122, v[192:193], off nt
	global_load_dword v123, v[190:191], off nt
	global_load_dword v124, v[196:197], off nt
	global_load_dword v125, v[194:195], off nt
	global_load_dword v126, v[200:201], off nt
	global_load_dword v127, v[198:199], off nt
	global_load_dword v128, v[204:205], off nt
	global_load_dword v129, v[202:203], off nt
	global_load_dword v130, v[208:209], off nt
	global_load_dword v131, v[206:207], off nt
	global_load_dword v132, v[212:213], off nt
	global_load_dword v133, v[210:211], off nt
	global_load_dword v134, v[216:217], off nt
	global_load_dword v135, v[214:215], off nt
	s_add_i32 s5, s5, 16
	s_add_i32 s6, s6, 16
	s_mov_b32 s7, 0
	v_mad_u64_u32 v[186:187], s[8:9], v11, s1, v[6:7]
	v_mad_u64_u32 v[188:189], s[8:9], v9, s1, v[6:7]
	v_mad_u64_u32 v[190:191], s[8:9], v71, s1, v[6:7]
	v_mad_u64_u32 v[192:193], s[8:9], v70, s1, v[6:7]
	v_mad_u64_u32 v[194:195], s[8:9], v73, s1, v[6:7]
	v_mad_u64_u32 v[196:197], s[8:9], v72, s1, v[6:7]
	v_mad_u64_u32 v[198:199], s[8:9], v75, s1, v[6:7]
	v_mad_u64_u32 v[200:201], s[8:9], v74, s1, v[6:7]
	v_mad_u64_u32 v[202:203], s[8:9], v77, s1, v[6:7]
	v_mad_u64_u32 v[204:205], s[8:9], v76, s1, v[6:7]
	v_mad_u64_u32 v[206:207], s[8:9], v79, s1, v[6:7]
	v_mad_u64_u32 v[208:209], s[8:9], v78, s1, v[6:7]
	v_mad_u64_u32 v[210:211], s[8:9], v81, s1, v[6:7]
	v_mad_u64_u32 v[212:213], s[8:9], v80, s1, v[6:7]
	v_mad_u64_u32 v[214:215], s[8:9], v83, s1, v[6:7]
	v_mad_u64_u32 v[216:217], s[8:9], v82, s1, v[6:7]
	s_waitcnt vmcnt(31)
	ds_write_b32 v38, v17
	s_waitcnt vmcnt(30)
	ds_write_b32 v40, v37
	s_waitcnt vmcnt(29)
	ds_write_b32 v42, v84
	s_waitcnt vmcnt(28)
	ds_write_b32 v44, v85
	s_waitcnt vmcnt(27)
	ds_write_b32 v46, v86
	s_waitcnt vmcnt(26)
	ds_write_b32 v48, v87
	s_waitcnt vmcnt(25)
	ds_write_b32 v50, v88
	s_waitcnt vmcnt(24)
	ds_write_b32 v52, v89
	s_waitcnt vmcnt(23)
	ds_write_b32 v54, v90
	s_waitcnt vmcnt(22)
	ds_write_b32 v56, v91
	s_waitcnt vmcnt(21)
	ds_write_b32 v58, v92
	s_waitcnt vmcnt(20)
	ds_write_b32 v60, v93
	s_waitcnt vmcnt(19)
	ds_write_b32 v62, v94
	s_waitcnt vmcnt(18)
	ds_write_b32 v64, v95
	s_waitcnt vmcnt(17)
	ds_write_b32 v66, v96
	s_waitcnt vmcnt(16)
	ds_write_b32 v68, v97
	s_waitcnt vmcnt(15)
	ds_write_b32 v186, v120
	s_waitcnt vmcnt(14)
	ds_write_b32 v188, v121
	s_waitcnt vmcnt(13)
	ds_write_b32 v190, v122
	s_waitcnt vmcnt(12)
	ds_write_b32 v192, v123
	s_waitcnt vmcnt(11)
	ds_write_b32 v194, v124
	s_waitcnt vmcnt(10)
	ds_write_b32 v196, v125
	s_waitcnt vmcnt(9)
	ds_write_b32 v198, v126
	s_waitcnt vmcnt(8)
	ds_write_b32 v200, v127
	s_waitcnt vmcnt(7)
	ds_write_b32 v202, v128
	s_waitcnt vmcnt(6)
	ds_write_b32 v204, v129
	s_waitcnt vmcnt(5)
	ds_write_b32 v206, v130
	s_waitcnt vmcnt(4)
	ds_write_b32 v208, v131
	s_waitcnt vmcnt(3)
	ds_write_b32 v210, v132
	s_waitcnt vmcnt(2)
	ds_write_b32 v212, v133
	s_waitcnt vmcnt(1)
	ds_write_b32 v214, v134
	s_waitcnt vmcnt(0)
	ds_write_b32 v216, v135
	s_waitcnt lgkmcnt(0)
	v_ashrrev_i32_e32 v17, 31, v16
	v_lshl_add_u64 v[2:3], v[16:17], 1, v[14:15]
	ds_read2_b32 v[16:17], v20 offset0:33 offset1:41
	ds_read2_b32 v[18:19], v20 offset1:8
	ds_read2_b32 v[38:39], v20 offset0:66 offset1:74
	ds_read2_b32 v[40:41], v20 offset0:99 offset1:107
	ds_read2_b32 v[42:43], v20 offset0:132 offset1:140
	ds_read2_b32 v[44:45], v20 offset0:165 offset1:173
	ds_read2_b32 v[46:47], v20 offset0:198 offset1:206
	ds_read2_b32 v[48:49], v20 offset0:231 offset1:239
	v_or_b32_e32 v7, v4, v185
	v_ashrrev_i32_e32 v9, 31, v4
	v_mov_b32_e32 v11, v5
	v_mul_lo_u32 v9, v9, v36
	v_mad_u64_u32 v[50:51], s[6:7], v7, v36, 0
	v_lshl_add_u64 v[2:3], v[2:3], 0, v[10:11]
	v_add_u32_e32 v51, v51, v9
	s_waitcnt lgkmcnt(6)
	v_cvt_pk_bf16_f32 v12, v18, v16
	s_waitcnt lgkmcnt(4)
	v_cvt_pk_bf16_f32 v13, v38, v40
	s_waitcnt lgkmcnt(2)
	v_cvt_pk_bf16_f32 v14, v42, v44
	s_waitcnt lgkmcnt(0)
	v_cvt_pk_bf16_f32 v15, v46, v48
	v_lshl_add_u64 v[50:51], v[50:51], 1, v[2:3]
	global_store_dwordx4 v[50:51], v[12:15], off sc1
	v_or_b32_e32 v7, v4, v21
	s_add_i32 s5, s0, 0x80
	v_cvt_pk_bf16_f32 v12, v19, v17
	v_cvt_pk_bf16_f32 v13, v39, v41
	v_cvt_pk_bf16_f32 v14, v43, v45
	v_cvt_pk_bf16_f32 v15, v47, v49
	v_mad_u64_u32 v[16:17], s[6:7], v7, v36, 0
	ds_read2_b32 v[18:19], v20 offset0:16 offset1:24
	ds_read2_b32 v[38:39], v20 offset0:49 offset1:57
	ds_read2_b32 v[40:41], v20 offset0:82 offset1:90
	ds_read2_b32 v[42:43], v20 offset0:115 offset1:123
	ds_read2_b32 v[44:45], v20 offset0:148 offset1:156
	ds_read2_b32 v[46:47], v20 offset0:181 offset1:189
	ds_read2_b32 v[48:49], v20 offset0:214 offset1:222
	ds_read2_b32 v[50:51], v20 offset0:247 offset1:255
	v_add_u32_e32 v17, v17, v9
	v_lshl_add_u64 v[16:17], v[16:17], 1, v[2:3]
	v_or_b32_e32 v7, v4, v22
	global_store_dwordx4 v[16:17], v[12:15], off sc1
	v_mad_u64_u32 v[16:17], s[6:7], v7, v36, 0
	v_add_u32_e32 v17, v17, v9
	s_waitcnt lgkmcnt(6)
	v_cvt_pk_bf16_f32 v12, v18, v38
	s_waitcnt lgkmcnt(4)
	v_cvt_pk_bf16_f32 v13, v40, v42
	s_waitcnt lgkmcnt(2)
	v_cvt_pk_bf16_f32 v14, v44, v46
	s_waitcnt lgkmcnt(0)
	v_cvt_pk_bf16_f32 v15, v48, v50
	v_lshl_add_u64 v[16:17], v[16:17], 1, v[2:3]
	v_or_b32_e32 v4, v4, v23
	global_store_dwordx4 v[16:17], v[12:15], off sc1
	v_mad_u64_u32 v[16:17], s[6:7], v4, v36, 0
	v_add_u32_e32 v17, v17, v9
	v_cvt_pk_bf16_f32 v12, v19, v39
	v_cvt_pk_bf16_f32 v13, v41, v43
	v_cvt_pk_bf16_f32 v14, v45, v47
	v_cvt_pk_bf16_f32 v15, v49, v51
	v_lshl_add_u64 v[2:3], v[16:17], 1, v[2:3]
	global_store_dwordx4 v[2:3], v[12:15], off sc1
	s_waitcnt lgkmcnt(0)
	s_cmpk_gt_i32 s0, 0x0
	s_mov_b32 s0, s5
	s_cbranch_scc0 .Lgu0e_BB0_1019

.Lgu0e_skip:
	s_cmpk_lt_u32 s78, 0x80
	s_cbranch_scc1 .Lgu0e_done
	s_cmpk_gt_u32 s78, 0xcf
	s_cbranch_scc1 .Lgu0e_done
	s_waitcnt vmcnt(0)
	s_barrier
	s_mov_b64 s[100:101], exec
	v_readlane_b32 s98, v219, 25
	v_readlane_b32 s99, v219, 26
	s_nop 1
	s_and_b64 s[98:99], s[100:101], s[98:99]
	s_mov_b64 exec, s[98:99]
	s_cbranch_execz .Lgu0e_noat
	v_readlane_b32 s98, v219, 27
	v_readlane_b32 s99, v219, 28
	v_mov_b32_e32 v0, 1
	v_mov_b32_e32 v1, 0x11c0
	s_nop 3
	global_atomic_add v1, v0, s[98:99]
.Lgu0e_noat:
	s_mov_b64 exec, s[100:101]
.Lgu0e_done:
	v_readlane_b32 s78, v219, 30
	s_nop 1
	s_cmpk_gt_i32 s78, 0x57f
	s_cbranch_scc1 .LBB0_693
	s_add_u32 s0, s56, 0x900000
	s_addc_u32 s1, s57, 0
	s_lshl_b32 s2, s78, 19
	s_lshr_b32 s5, s4, 6
	s_bfe_u32 s22, s4, 0x10006
	s_lshr_b32 s23, s4, 7
	s_and_b32 s2, s2, 0xf80000
	s_add_u32 s16, s30, s2
	s_addc_u32 s17, s31, 0
	s_lshl_b32 s2, s78, 2
	s_and_b32 s2, s2, 0xffffff80
	s_ashr_i32 s3, s2, 31
	s_mov_b32 s93, 0
	s_lshl_b64 s[6:7], s[2:3], 11
	s_lshl_b32 s92, s5, 5
	s_lshl_b32 s2, s5, 12
	s_add_i32 s3, s2, 0
	s_lshl_b64 s[14:15], s[92:93], 11
	s_add_u32 s8, s16, s14
	s_addc_u32 s9, s17, s15
	s_or_b32 s10, s92, 8
	s_mov_b32 s11, s93
	s_lshl_b64 s[36:37], s[10:11], 11
	s_add_u32 s10, s16, s36
	v_mov_b32_e32 v0, v178
	v_mov_b32_e32 v1, v179
	s_mov_b32 m0, s3
	s_addc_u32 s11, s17, s37
	s_or_b32 s12, s92, 16
	s_mov_b32 s13, s93
	s_barrier
	s_lshl_b64 s[38:39], s[12:13], 11
	global_load_lds_dwordx4 v0, s[8:9]
	s_add_i32 m0, s3, 0x400
	s_add_u32 s12, s16, s38
	s_addc_u32 s13, s17, s39
	s_or_b32 s92, s92, 24
	global_load_lds_dwordx4 v1, s[10:11]
	s_add_i32 m0, s3, 0x800
	s_lshl_b64 s[40:41], s[92:93], 11
	s_add_u32 s18, s16, s40
	global_load_lds_dwordx4 v0, s[12:13]
	s_addc_u32 s19, s17, s41
	s_add_i32 m0, s3, 0xc00
	s_add_u32 s17, s0, s6
	s_addc_u32 s21, s1, s7
	s_lshl_b32 s16, s5, 11
	s_lshl_b32 s92, s5, 4
	s_sub_i32 s24, s3, s16
	global_load_lds_dwordx4 v1, s[18:19]
	s_add_i32 m0, s24, 0x8000
	s_lshl_b64 s[42:43], s[92:93], 11
	s_add_u32 s6, s17, s42
	s_addc_u32 s7, s21, s43
	s_or_b32 s92, s92, 8
	s_lshl_b64 s[44:45], s[92:93], 11
	s_add_u32 s20, s17, s44
	global_load_lds_dwordx4 v0, s[6:7]
	s_addc_u32 s21, s21, s45
	s_add_i32 m0, s24, 0x8400
	v_mov_b32_e32 v150, v178
	v_mov_b32_e32 v0, v179
	v_mov_b32_e32 v151, 0
	global_load_lds_dwordx4 v1, s[20:21]
	s_mov_b64 s[46:47], 0x80
	v_lshl_add_u64 v[2:3], s[8:9], 0, v[150:151]
	s_add_i32 m0, s3, 0xc000
	v_lshl_add_u64 v[2:3], v[2:3], 0, s[46:47]
	v_mov_b32_e32 v1, v151
	global_load_lds_dwordx4 v[2:3], off
	v_lshl_add_u64 v[2:3], s[10:11], 0, v[0:1]
	v_lshl_add_u64 v[2:3], v[2:3], 0, s[46:47]
	s_add_i32 m0, s3, 0xc400
	s_add_i32 s8, s16, 0
	global_load_lds_dwordx4 v[2:3], off
	v_lshl_add_u64 v[2:3], s[12:13], 0, v[150:151]
	v_lshl_add_u64 v[2:3], v[2:3], 0, s[46:47]
	s_add_i32 m0, s3, 0xc800
	v_lshl_or_b32 v156, s23, 6, v167
	global_load_lds_dwordx4 v[2:3], off
	v_lshl_add_u64 v[2:3], s[18:19], 0, v[0:1]
	v_lshl_add_u64 v[2:3], v[2:3], 0, s[46:47]
	s_add_i32 m0, s3, 0xcc00
	v_lshl_add_u64 v[0:1], s[20:21], 0, v[0:1]
	global_load_lds_dwordx4 v[2:3], off
	v_lshl_add_u64 v[2:3], s[6:7], 0, v[150:151]
	s_add_i32 m0, s8, 0x14000
	v_lshl_add_u64 v[2:3], v[2:3], 0, s[46:47]
	global_load_lds_dwordx4 v[2:3], off
	v_lshl_add_u64 v[0:1], v[0:1], 0, s[46:47]
	s_add_i32 m0, s8, 0x14400
	s_cmpk_gt_u32 s4, 0xff
	global_load_lds_dwordx4 v[0:1], off
	s_cselect_b64 s[48:49], -1, 0
	s_lshl_b32 s92, s5, 15
	s_lshl_b32 s4, s5, 14
	s_lshl_b32 s17, s22, 13
	s_lshl_b32 s18, s23, 13
	s_lshl_b32 s6, s22, 6
	v_readlane_b32 s8, v219, 33
	v_readlane_b32 s9, v219, 34
	s_add_u32 s6, s8, s6
	s_addc_u32 s7, s9, 0
	s_add_u32 s19, s56, s14
	s_addc_u32 s22, s57, s15
	s_lshl_b32 s23, s78, 8
	s_lshl_b32 s24, s58, 8
	s_add_u32 s25, s56, s42
	s_addc_u32 s26, s57, s43
	s_lshl_b64 s[50:51], s[92:93], 1
	s_mov_b32 s5, s93
	v_add_u32_e32 v0, 12, v146
	v_cmp_eq_u32_e32 vcc, 0, v171
	s_add_u32 s27, s56, s50
	v_xor_b32_e32 v1, v147, v170
	v_cndmask_b32_e32 v0, v0, v146, vcc
	s_addc_u32 s28, s57, s51
	s_lshl_b64 s[68:69], s[4:5], 1
	v_lshlrev_b32_e32 v157, 4, v1
	v_bitop3_b32 v1, v147, v170, 4 bitop3:0x36
	v_lshlrev_b32_e32 v150, 1, v0
	s_add_u32 s29, s56, s68
	v_lshlrev_b32_e32 v158, 4, v1
	v_lshl_add_u64 v[152:153], s[6:7], 0, v[150:151]
	s_addc_u32 s33, s57, s69
	s_mov_b64 s[4:5], -1
	s_mov_b64 s[70:71], 0x100
	s_mov_b64 s[72:73], 0x3400180
	s_mov_b64 s[74:75], 0x3404180
	s_mov_b64 s[76:77], 0x3408180
	s_mov_b32 s61, s78
	s_mov_b64 s[78:79], 0x340c180
	s_mov_b64 s[80:81], 0x900180
	s_mov_b64 s[82:83], 0x904180
	s_mov_b64 s[84:85], 0x4000
	s_movk_i32 s60, 0x1600
	s_branch .LBB0_632

.Lgb7_spin2:
	global_load_dword v2, v1, s[0:1] sc1
	s_waitcnt vmcnt(0)
	v_readfirstlane_b32 s13, v2
	s_nop 1
	s_cmp_ge_u32 s13, 80
	s_cbranch_scc1 .Lgb7_done2
	s_sleep 4
	s_add_i32 s15, s15, 1
	s_cmp_lt_u32 s15, 0x200000
	s_cbranch_scc1 .Lgb7_spin2
